# v84 + P0 x->bf16 row loop software-pipelined: two rows in flight per wave (unroll x2, second register set v100-119)
# baseline (speedup 1.0000x reference)
.LBB0_364:
	s_ashr_i32 s4, s2, 31
	s_lshr_b32 s4, s4, 17
	s_add_i32 s4, s2, s4
	s_and_b32 s4, s4, 0xffff8000
	s_sub_i32 s4, s2, s4
	s_ashr_i32 s5, s4, 31
	s_lshl_b64 s[6:7], s[4:5], 12
	v_lshl_add_u64 v[12:13], v[22:23], 0, s[6:7]
	global_load_dwordx4 v[0:3], v[12:13], off nt
	global_load_dwordx4 v[4:7], v[12:13], off offset:1024 nt
	global_load_dwordx4 v[8:11], v[12:13], off offset:2048 nt
	s_nop 0
	global_load_dwordx4 v[12:15], v[12:13], off offset:3072 nt
	s_lshl_b64 s[10:11], s[4:5], 10
	v_lshl_add_u64 v[16:17], v[24:25], 0, s[10:11]
	global_load_dwordx4 v[16:19], v[16:17], off nt
	s_mov_b32 s96, s4
.Lx_loop:
	s_add_i32 s98, s2, s3
	s_cmpk_gt_i32 s98, 0x7fff
	s_cbranch_scc1 .Lx_nb_drain
	s_ashr_i32 s4, s98, 31
	s_lshr_b32 s4, s4, 17
	s_add_i32 s4, s98, s4
	s_and_b32 s4, s4, 0xffff8000
	s_sub_i32 s4, s98, s4
	s_ashr_i32 s5, s4, 31
	s_lshl_b64 s[6:7], s[4:5], 12
	v_lshl_add_u64 v[112:113], v[22:23], 0, s[6:7]
	global_load_dwordx4 v[100:103], v[112:113], off nt
	global_load_dwordx4 v[104:107], v[112:113], off offset:1024 nt
	global_load_dwordx4 v[108:111], v[112:113], off offset:2048 nt
	s_nop 0
	global_load_dwordx4 v[112:115], v[112:113], off offset:3072 nt
	s_lshl_b64 s[10:11], s[4:5], 10
	v_lshl_add_u64 v[116:117], v[24:25], 0, s[10:11]
	global_load_dwordx4 v[116:119], v[116:117], off nt
	s_mov_b32 s97, s4
.Lx_nb:
	s_waitcnt vmcnt(5)
	v_mul_f32_e32 v36, v1, v1
	v_mul_f32_e32 v37, v3, v3
	v_mul_f32_e32 v38, v5, v5
	v_mul_f32_e32 v39, v7, v7
	v_mul_f32_e32 v40, v9, v9
	v_mul_f32_e32 v41, v11, v11
	v_fmac_f32_e32 v36, v0, v0
	v_fmac_f32_e32 v37, v2, v2
	v_fmac_f32_e32 v38, v4, v4
	v_fmac_f32_e32 v39, v6, v6
	v_mul_f32_e32 v42, v13, v13
	v_mul_f32_e32 v43, v15, v15
	v_fmac_f32_e32 v40, v8, v8
	v_fmac_f32_e32 v41, v10, v10
	v_add_f32_e32 v36, v36, v37
	v_add_f32_e32 v37, v38, v39
	v_fmac_f32_e32 v42, v12, v12
	v_fmac_f32_e32 v43, v14, v14
	v_add_f32_e32 v38, v40, v41
	v_add_f32_e32 v36, v36, v37
	v_add_f32_e32 v36, v36, v38
	v_add_f32_e32 v37, v42, v43
	v_add_f32_e32 v36, v36, v37
	ds_bpermute_b32 v37, v30, v36
	s_waitcnt lgkmcnt(0)
	v_add_f32_e32 v36, v36, v37
	ds_bpermute_b32 v37, v31, v36
	s_waitcnt lgkmcnt(0)
	v_add_f32_e32 v36, v36, v37
	ds_bpermute_b32 v37, v32, v36
	s_waitcnt lgkmcnt(0)
	v_add_f32_e32 v36, v36, v37
	ds_bpermute_b32 v37, v33, v36
	s_waitcnt lgkmcnt(0)
	v_add_f32_e32 v36, v36, v37
	ds_bpermute_b32 v37, v34, v36
	s_waitcnt lgkmcnt(0)
	v_add_f32_e32 v36, v36, v37
	ds_bpermute_b32 v37, v35, v36
	s_mov_b32 s4, s96
	s_ashr_i32 s5, s4, 31
	s_and_saveexec_b64 s[12:13], vcc
	s_cbranch_execz .Lx_skip_a
	s_waitcnt lgkmcnt(0)
	v_add_f32_e32 v36, v36, v37
	v_fmamk_f32 v36, v36, 0x3a800000, v20
	v_mul_f32_e32 v37, 0x4b800000, v36
	v_cmp_gt_f32_e64 s[6:7], s15, v36
	s_lshl_b64 s[28:29], s[4:5], 2
	s_add_u32 s28, s9, s28
	v_cndmask_b32_e64 v36, v36, v37, s[6:7]
	v_rsq_f32_e32 v36, v36
	s_addc_u32 s29, s14, s29
	v_mul_f32_e32 v37, 0x45800000, v36
	v_cndmask_b32_e64 v36, v36, v37, s[6:7]
	global_store_dword v21, v36, s[28:29]
.Lx_skip_a:
	s_or_b64 exec, exec, s[12:13]
	s_waitcnt lgkmcnt(0)
	s_lshl_b64 s[10:11], s[4:5], 10
	v_lshl_add_u64 v[36:37], s[10:11], 1, v[26:27]
	v_cvt_pk_bf16_f32 v0, v0, v1
	v_cvt_pk_bf16_f32 v1, v2, v3
	global_store_dwordx2 v[36:37], v[0:1], off
	v_cvt_pk_bf16_f32 v0, v4, v5
	v_cvt_pk_bf16_f32 v1, v6, v7
	global_store_dwordx2 v[36:37], v[0:1], off offset:512
	v_cvt_pk_bf16_f32 v0, v8, v9
	v_cvt_pk_bf16_f32 v1, v10, v11
	s_lshl_b64 s[4:5], s[4:5], 8
	global_store_dwordx2 v[36:37], v[0:1], off offset:1024
	v_cvt_pk_bf16_f32 v0, v12, v13
	v_cvt_pk_bf16_f32 v1, v14, v15
	global_store_dwordx2 v[36:37], v[0:1], off offset:1536
	v_cvt_pk_bf16_f32 v0, v16, v17
	v_cvt_pk_bf16_f32 v1, v18, v19
	v_lshl_add_u64 v[38:39], s[4:5], 1, v[28:29]
	global_store_dwordx2 v[38:39], v[0:1], off
	s_add_i32 s2, s2, s3
	s_cmpk_gt_i32 s2, 0x7fff
	s_cbranch_scc1 .LBB0_366
	s_add_i32 s98, s2, s3
	s_cmpk_gt_i32 s98, 0x7fff
	s_cbranch_scc1 .Lx_na
	s_ashr_i32 s4, s98, 31
	s_lshr_b32 s4, s4, 17
	s_add_i32 s4, s98, s4
	s_and_b32 s4, s4, 0xffff8000
	s_sub_i32 s4, s98, s4
	s_ashr_i32 s5, s4, 31
	s_lshl_b64 s[6:7], s[4:5], 12
	v_lshl_add_u64 v[12:13], v[22:23], 0, s[6:7]
	global_load_dwordx4 v[0:3], v[12:13], off nt
	global_load_dwordx4 v[4:7], v[12:13], off offset:1024 nt
	global_load_dwordx4 v[8:11], v[12:13], off offset:2048 nt
	s_nop 0
	global_load_dwordx4 v[12:15], v[12:13], off offset:3072 nt
	s_lshl_b64 s[10:11], s[4:5], 10
	v_lshl_add_u64 v[16:17], v[24:25], 0, s[10:11]
	global_load_dwordx4 v[16:19], v[16:17], off nt
	s_mov_b32 s96, s4
.Lx_na:
	s_waitcnt vmcnt(5)
	v_mul_f32_e32 v36, v101, v101
	v_mul_f32_e32 v37, v103, v103
	v_mul_f32_e32 v38, v105, v105
	v_mul_f32_e32 v39, v107, v107
	v_mul_f32_e32 v40, v109, v109
	v_mul_f32_e32 v41, v111, v111
	v_fmac_f32_e32 v36, v100, v100
	v_fmac_f32_e32 v37, v102, v102
	v_fmac_f32_e32 v38, v104, v104
	v_fmac_f32_e32 v39, v106, v106
	v_mul_f32_e32 v42, v113, v113
	v_mul_f32_e32 v43, v115, v115
	v_fmac_f32_e32 v40, v108, v108
	v_fmac_f32_e32 v41, v110, v110
	v_add_f32_e32 v36, v36, v37
	v_add_f32_e32 v37, v38, v39
	v_fmac_f32_e32 v42, v112, v112
	v_fmac_f32_e32 v43, v114, v114
	v_add_f32_e32 v38, v40, v41
	v_add_f32_e32 v36, v36, v37
	v_add_f32_e32 v36, v36, v38
	v_add_f32_e32 v37, v42, v43
	v_add_f32_e32 v36, v36, v37
	ds_bpermute_b32 v37, v30, v36
	s_waitcnt lgkmcnt(0)
	v_add_f32_e32 v36, v36, v37
	ds_bpermute_b32 v37, v31, v36
	s_waitcnt lgkmcnt(0)
	v_add_f32_e32 v36, v36, v37
	ds_bpermute_b32 v37, v32, v36
	s_waitcnt lgkmcnt(0)
	v_add_f32_e32 v36, v36, v37
	ds_bpermute_b32 v37, v33, v36
	s_waitcnt lgkmcnt(0)
	v_add_f32_e32 v36, v36, v37
	ds_bpermute_b32 v37, v34, v36
	s_waitcnt lgkmcnt(0)
	v_add_f32_e32 v36, v36, v37
	ds_bpermute_b32 v37, v35, v36
	s_mov_b32 s4, s97
	s_ashr_i32 s5, s4, 31
	s_and_saveexec_b64 s[12:13], vcc
	s_cbranch_execz .Lx_skip_b
	s_waitcnt lgkmcnt(0)
	v_add_f32_e32 v36, v36, v37
	v_fmamk_f32 v36, v36, 0x3a800000, v20
	v_mul_f32_e32 v37, 0x4b800000, v36
	v_cmp_gt_f32_e64 s[6:7], s15, v36
	s_lshl_b64 s[28:29], s[4:5], 2
	s_add_u32 s28, s9, s28
	v_cndmask_b32_e64 v36, v36, v37, s[6:7]
	v_rsq_f32_e32 v36, v36
	s_addc_u32 s29, s14, s29
	v_mul_f32_e32 v37, 0x45800000, v36
	v_cndmask_b32_e64 v36, v36, v37, s[6:7]
	global_store_dword v21, v36, s[28:29]
.Lx_skip_b:
	s_or_b64 exec, exec, s[12:13]
	s_waitcnt lgkmcnt(0)
	s_lshl_b64 s[10:11], s[4:5], 10
	v_lshl_add_u64 v[36:37], s[10:11], 1, v[26:27]
	v_cvt_pk_bf16_f32 v100, v100, v101
	v_cvt_pk_bf16_f32 v101, v102, v103
	global_store_dwordx2 v[36:37], v[100:101], off
	v_cvt_pk_bf16_f32 v100, v104, v105
	v_cvt_pk_bf16_f32 v101, v106, v107
	global_store_dwordx2 v[36:37], v[100:101], off offset:512
	v_cvt_pk_bf16_f32 v100, v108, v109
	v_cvt_pk_bf16_f32 v101, v110, v111
	s_lshl_b64 s[4:5], s[4:5], 8
	global_store_dwordx2 v[36:37], v[100:101], off offset:1024
	v_cvt_pk_bf16_f32 v100, v112, v113
	v_cvt_pk_bf16_f32 v101, v114, v115
	global_store_dwordx2 v[36:37], v[100:101], off offset:1536
	v_cvt_pk_bf16_f32 v100, v116, v117
	v_cvt_pk_bf16_f32 v101, v118, v119
	v_lshl_add_u64 v[38:39], s[4:5], 1, v[28:29]
	global_store_dwordx2 v[38:39], v[100:101], off
	s_add_i32 s2, s2, s3
	s_cmpk_gt_i32 s2, 0x7fff
	s_cbranch_scc0 .Lx_loop
	s_branch .LBB0_366
